# diff-attn exp stream re-sorted by dependency so P groups finish earlier; 48 of 64 PV MFMAs interleaved
# speedup vs baseline: 1.0590x; 1.0000x over previous
; DI f4 mfma16(h8 a, h8 b, f4 c) { return __builtin_amdgcn_mfma_f32_16x16x32_f16(a, b, c, 0, 0, 0); }
; template <int DQK, bool BIAS>
; __device__ __forceinline__ void attn_pass(const hf* __restrict__ Q, int ldq, const hf* __restrict__ Kp, int ldk, const hf* __restrict__ VT,
;                                           int s0, int L, int q0, float scale_l2, const float* sBias, f4 (&oacc)[8][4], char* smem) {
;     ...
;       float ps = 0.f;
; #pragma unroll
;       for (int mk = 0; mk < 4; ++mk)
; #pragma unroll
;         for (int j = 0; j < 4; ++j) {
;           float pe = BIAS ? __builtin_amdgcn_exp2f(sacc[mk][nq][j] - mnew) : __builtin_amdgcn_exp2f(sacc[mk][nq][j] * scale_l2 - mnew);
;           sacc[mk][nq][j] = pe; ps += pe;
;         }
;       lrun[nq] += ps;
; #pragma unroll
;       for (int s2 = 0; s2 < 2; ++s2)
; #pragma unroll
;         for (int i = 0; i < 8; ++i) pf[nq][s2][i] = (hf)sacc[2 * s2 + (i >> 2)][nq][i & 3];
;     }
; #pragma unroll
;     for (int mh = 0; mh < 2; ++mh) {
;       h8 vf[4][2];
; #pragma unroll
;       for (int m4 = 0; m4 < 4; ++m4)
; #pragma unroll
;         for (int s2 = 0; s2 < 2; ++s2) {
;           h4 v0 = *(const h4*)(sVT + ((mh * 4 + m4) * 16 + fr) * 72 + s2 * 32 + fq * 4);
;           h4 v1 = *(const h4*)(sVT + ((mh * 4 + m4) * 16 + fr) * 72 + s2 * 32 + 16 + fq * 4);
;           vf[m4][s2] = __builtin_shufflevector(v0, v1, 0, 1, 2, 3, 4, 5, 6, 7);
;         }
; #pragma unroll
;       for (int nq = 0; nq < 4; ++nq)
; #pragma unroll
;         for (int m4 = 0; m4 < 4; ++m4) {
;           oacc[mh * 4 + m4][nq] = mfma16(vf[m4][0], pf[nq][0], oacc[mh * 4 + m4][nq]);
;           oacc[mh * 4 + m4][nq] = mfma16(vf[m4][1], pf[nq][1], oacc[mh * 4 + m4][nq]);
;         }
.LBB0_1976:
	v_lshlrev_b32_e32 v113, 1, v238
	v_lshlrev_b32_e32 v114, 1, v237
	v_add3_u32 v113, s95, v113, v114
	v_add_u32_e32 v114, 0x3000, v113
	ds_read2_b64 a[128:131], v114 offset0:128 offset1:132
	v_add_u32_e32 v114, 0x3000, v113
	ds_read2_b64 a[132:135], v114 offset0:136 offset1:140
	v_sub_f32_e32 v48, v128, v144
	v_exp_f32_e32 v48, v48
	v_sub_f32_e32 v50, v129, v144
	v_exp_f32_e32 v50, v50
	v_add_u32_e32 v114, 0x3800, v113
	ds_read2_b64 a[136:139], v114 offset0:160 offset1:164
	v_sub_f32_e32 v51, v130, v144
	v_exp_f32_e32 v51, v51
	v_sub_f32_e32 v52, v131, v144
	v_exp_f32_e32 v52, v52
	v_add_u32_e32 v114, 0x3800, v113
	ds_read2_b64 a[140:143], v114 offset0:168 offset1:172
	v_sub_f32_e32 v53, v140, v144
	v_add_f32_e32 v49, 0, v48
	v_exp_f32_e32 v53, v53
	v_sub_f32_e32 v54, v141, v144
	v_add_u32_e32 v114, 0x4000, v113
	ds_read2_b64 a[144:147], v114 offset0:192 offset1:196
	v_add_f32_e32 v49, v50, v49
	v_exp_f32_e32 v54, v54
	v_sub_f32_e32 v55, v142, v144
	v_add_f32_e32 v49, v51, v49
	v_add_u32_e32 v114, 0x4000, v113
	ds_read2_b64 a[148:151], v114 offset0:200 offset1:204
	v_exp_f32_e32 v55, v55
	v_sub_f32_e32 v56, v143, v144
	v_add_f32_e32 v49, v52, v49
	v_exp_f32_e32 v56, v56
	v_add_u32_e32 v114, 0x4800, v113
	ds_read2_b64 a[152:155], v114 offset0:224 offset1:228
	v_sub_f32_e32 v57, v136, v144
	v_add_f32_e32 v49, v53, v49
	v_exp_f32_e32 v57, v57
	v_sub_f32_e32 v58, v137, v144
	v_add_u32_e32 v114, 0x4800, v113
	ds_read2_b64 a[156:159], v114 offset0:232 offset1:236
	v_add_f32_e32 v49, v54, v49
	v_exp_f32_e32 v58, v58
	v_sub_f32_e32 v59, v138, v144
	v_add_f32_e32 v49, v55, v49
	v_add_u32_e32 v114, 0x5800, v113
	ds_read2_b64 a[160:163], v114 offset1:4
	v_exp_f32_e32 v59, v59
	v_sub_f32_e32 v60, v139, v144
	v_add_f32_e32 v49, v56, v49
	v_exp_f32_e32 v60, v60
	v_add_u32_e32 v114, 0x5800, v113
	ds_read2_b64 a[164:167], v114 offset0:8 offset1:12
	v_sub_f32_e32 v61, v132, v144
	v_add_f32_e32 v49, v57, v49
	v_exp_f32_e32 v61, v61
	v_sub_f32_e32 v62, v133, v144
	v_add_u32_e32 v114, 0x6000, v113
	ds_read2_b64 a[168:171], v114 offset0:32 offset1:36
	v_add_f32_e32 v49, v58, v49
	v_exp_f32_e32 v62, v62
	v_sub_f32_e32 v63, v134, v144
	v_add_f32_e32 v49, v59, v49
	v_add_u32_e32 v114, 0x6000, v113
	ds_read2_b64 a[172:175], v114 offset0:40 offset1:44
	v_exp_f32_e32 v63, v63
	v_sub_f32_e32 v64, v135, v144
	v_add_f32_e32 v49, v60, v49
	v_exp_f32_e32 v64, v64
	v_add_u32_e32 v114, 0x6800, v113
	ds_read2_b64 a[176:179], v114 offset0:64 offset1:68
	v_add_f32_e32 v49, v61, v49
	v_add_f32_e32 v49, v62, v49
	v_add_f32_e32 v49, v63, v49
	v_cvt_pk_f16_f32 v55, v55, v56
	v_add_u32_e32 v114, 0x6800, v113
	ds_read2_b64 a[180:183], v114 offset0:72 offset1:76
	v_add_f32_e32 v49, v64, v49
	v_cvt_pk_f16_f32 v54, v53, v54
	v_cvt_pk_f16_f32 v53, v51, v52
	v_cvt_pk_f16_f32 v52, v48, v50
	v_add_u32_e32 v114, 0x7000, v113
	ds_read2_b64 a[184:187], v114 offset0:96 offset1:100
	v_cvt_pk_f16_f32 v48, v57, v58
	v_add_f32_e32 v242, v49, v242
	v_cvt_pk_f16_f32 v49, v59, v60
	v_cvt_pk_f16_f32 v50, v61, v62
	v_add_u32_e32 v114, 0x7000, v113
	ds_read2_b64 a[188:191], v114 offset0:104 offset1:108
	v_cvt_pk_f16_f32 v51, v63, v64
	v_sub_f32_e32 v56, v80, v160
	v_exp_f32_e32 v56, v56
	s_waitcnt lgkmcnt(0)
	v_mfma_f32_16x16x32_f16 a[12:15], a[128:131], v[52:55], a[12:15]
	v_sub_f32_e32 v58, v81, v160
	v_exp_f32_e32 v58, v58
	v_mfma_f32_16x16x32_f16 a[28:31], a[136:139], v[52:55], a[28:31]
	v_sub_f32_e32 v59, v82, v160
	v_exp_f32_e32 v59, v59
	v_mfma_f32_16x16x32_f16 a[40:43], a[144:147], v[52:55], a[40:43]
	v_sub_f32_e32 v60, v83, v160
	v_exp_f32_e32 v60, v60
	v_mfma_f32_16x16x32_f16 a[56:59], a[152:155], v[52:55], a[56:59]
	v_sub_f32_e32 v61, v92, v160
	v_add_f32_e32 v57, 0, v56
	v_mfma_f32_16x16x32_f16 a[12:15], a[132:135], v[48:51], a[12:15]
	v_exp_f32_e32 v61, v61
	v_sub_f32_e32 v62, v93, v160
	v_mfma_f32_16x16x32_f16 a[28:31], a[140:143], v[48:51], a[28:31]
	v_add_f32_e32 v57, v58, v57
	v_exp_f32_e32 v62, v62
	v_mfma_f32_16x16x32_f16 a[40:43], a[148:151], v[48:51], a[40:43]
	v_sub_f32_e32 v63, v94, v160
	v_add_f32_e32 v57, v59, v57
	v_mfma_f32_16x16x32_f16 a[56:59], a[156:159], v[48:51], a[56:59]
	v_exp_f32_e32 v63, v63
	v_sub_f32_e32 v64, v95, v160
	v_mfma_f32_16x16x32_f16 a[72:75], a[160:163], v[52:55], a[72:75]
	v_sub_f32_e32 v32, v32, v176
	v_add_f32_e32 v57, v60, v57
	v_mfma_f32_16x16x32_f16 a[88:91], a[168:171], v[52:55], a[88:91]
	v_exp_f32_e32 v64, v64
	v_exp_f32_e32 v32, v32
	v_mfma_f32_16x16x32_f16 a[108:111], a[176:179], v[52:55], a[108:111]
	v_sub_f32_e32 v33, v33, v176
	v_add_f32_e32 v57, v61, v57
	v_mfma_f32_16x16x32_f16 a[120:123], a[184:187], v[52:55], a[120:123]
	v_exp_f32_e32 v33, v33
	v_sub_f32_e32 v34, v34, v176
	v_mfma_f32_16x16x32_f16 a[72:75], a[164:167], v[48:51], a[72:75]
	v_add_f32_e32 v57, v62, v57
	v_exp_f32_e32 v34, v34
	v_mfma_f32_16x16x32_f16 a[88:91], a[172:175], v[48:51], a[88:91]
	v_sub_f32_e32 v35, v35, v176
	v_add_f32_e32 v57, v63, v57
	v_mfma_f32_16x16x32_f16 a[108:111], a[180:183], v[48:51], a[108:111]
	v_exp_f32_e32 v35, v35
	v_sub_f32_e32 v44, v44, v176
	v_mfma_f32_16x16x32_f16 a[120:123], a[188:191], v[48:51], a[120:123]
	v_add_f32_e32 v57, v64, v57
	v_sub_f32_e32 v65, v84, v160
	v_sub_f32_e32 v66, v85, v160
	v_cvt_pk_f16_f32 v63, v63, v64
	v_add_f32_e32 v64, 0, v32
	v_exp_f32_e32 v44, v44
	v_sub_f32_e32 v45, v45, v176
	v_exp_f32_e32 v65, v65
	v_exp_f32_e32 v66, v66
	v_add_f32_e32 v64, v33, v64
	v_exp_f32_e32 v45, v45
	v_sub_f32_e32 v46, v46, v176
	v_add_f32_e32 v64, v34, v64
	v_exp_f32_e32 v46, v46
	v_sub_f32_e32 v47, v47, v176
	v_add_f32_e32 v64, v35, v64
	v_exp_f32_e32 v47, v47
	v_sub_f32_e32 v40, v40, v176
	v_add_f32_e32 v64, v44, v64
; DI f4 mfma16(h8 a, h8 b, f4 c) { return __builtin_amdgcn_mfma_f32_16x16x32_f16(a, b, c, 0, 0, 0); }
; template <int DQK, bool BIAS>
; __device__ __forceinline__ void attn_pass(const hf* __restrict__ Q, int ldq, const hf* __restrict__ Kp, int ldk, const hf* __restrict__ VT,
;                                           int s0, int L, int q0, float scale_l2, const float* sBias, f4 (&oacc)[8][4], char* smem) {
;     ...
;       float ps = 0.f;
; #pragma unroll
;       for (int mk = 0; mk < 4; ++mk)
; #pragma unroll
;         for (int j = 0; j < 4; ++j) {
;           float pe = BIAS ? __builtin_amdgcn_exp2f(sacc[mk][nq][j] - mnew) : __builtin_amdgcn_exp2f(sacc[mk][nq][j] * scale_l2 - mnew);
;           sacc[mk][nq][j] = pe; ps += pe;
;         }
;       lrun[nq] += ps;
; #pragma unroll
;       for (int s2 = 0; s2 < 2; ++s2)
; #pragma unroll
;         for (int i = 0; i < 8; ++i) pf[nq][s2][i] = (hf)sacc[2 * s2 + (i >> 2)][nq][i & 3];
;     }
; #pragma unroll
;     for (int mh = 0; mh < 2; ++mh) {
;       h8 vf[4][2];
; #pragma unroll
;       for (int m4 = 0; m4 < 4; ++m4)
; #pragma unroll
;         for (int s2 = 0; s2 < 2; ++s2) {
;           h4 v0 = *(const h4*)(sVT + ((mh * 4 + m4) * 16 + fr) * 72 + s2 * 32 + fq * 4);
;           h4 v1 = *(const h4*)(sVT + ((mh * 4 + m4) * 16 + fr) * 72 + s2 * 32 + 16 + fq * 4);
;           vf[m4][s2] = __builtin_shufflevector(v0, v1, 0, 1, 2, 3, 4, 5, 6, 7);
;         }
; #pragma unroll
;       for (int nq = 0; nq < 4; ++nq)
; #pragma unroll
;         for (int m4 = 0; m4 < 4; ++m4) {
;           oacc[mh * 4 + m4][nq] = mfma16(vf[m4][0], pf[nq][0], oacc[mh * 4 + m4][nq]);
;           oacc[mh * 4 + m4][nq] = mfma16(vf[m4][1], pf[nq][1], oacc[mh * 4 + m4][nq]);
;         }
;     }
;     __syncthreads();
	v_exp_f32_e32 v40, v40
	v_sub_f32_e32 v41, v41, v176
	v_add_f32_e32 v57, v65, v57
	v_cvt_pk_f16_f32 v62, v61, v62
	v_cvt_pk_f16_f32 v61, v59, v60
	v_cvt_pk_f16_f32 v60, v56, v58
	v_cvt_pk_f16_f32 v56, v65, v66
	v_add_f32_e32 v64, v45, v64
	v_exp_f32_e32 v65, v41
	v_add_f32_e32 v64, v46, v64
	v_add_f32_e32 v64, v47, v64
	v_add_f32_e32 v64, v40, v64
	v_sub_f32_e32 v42, v42, v176
	v_add_f32_e32 v41, v65, v64
	v_exp_f32_e32 v64, v42
	v_sub_f32_e32 v42, v43, v176
	v_add_f32_e32 v57, v66, v57
	v_exp_f32_e32 v66, v42
	v_sub_f32_e32 v36, v36, v176
	v_sub_f32_e32 v37, v37, v176
	v_exp_f32_e32 v36, v36
	v_exp_f32_e32 v37, v37
	v_sub_f32_e32 v38, v38, v176
	v_sub_f32_e32 v39, v39, v176
	v_cvt_pk_f16_f32 v47, v46, v47
	v_cvt_pk_f16_f32 v46, v44, v45
	v_cvt_pk_f16_f32 v44, v32, v33
	v_add_f32_e32 v41, v64, v41
	v_exp_f32_e32 v38, v38
	v_exp_f32_e32 v39, v39
	v_cvt_pk_f16_f32 v45, v34, v35
	v_add_f32_e32 v41, v66, v41
	v_add_f32_e32 v41, v36, v41
	v_cvt_pk_f16_f32 v42, v36, v37
	v_add_f32_e32 v41, v37, v41
	v_add_f32_e32 v41, v38, v41
	v_cvt_pk_f16_f32 v43, v38, v39
	v_add_f32_e32 v41, v39, v41
	v_add_f32_e32 v245, v41, v245
	v_cvt_pk_f16_f32 v41, v64, v66
	v_cvt_pk_f16_f32 v40, v40, v65
	v_sub_f32_e32 v67, v86, v160
	v_exp_f32_e32 v67, v67
	v_mfma_f32_16x16x32_f16 a[0:3], a[128:131], v[44:47], a[0:3]
	v_sub_f32_e32 v68, v87, v160
	v_exp_f32_e32 v68, v68
	v_mfma_f32_16x16x32_f16 a[8:11], a[136:139], v[44:47], a[8:11]
	v_sub_f32_e32 v69, v88, v160
	v_exp_f32_e32 v69, v69
	v_mfma_f32_16x16x32_f16 a[24:27], a[144:147], v[44:47], a[24:27]
	v_sub_f32_e32 v70, v89, v160
	v_exp_f32_e32 v70, v70
	v_mfma_f32_16x16x32_f16 a[44:47], a[152:155], v[44:47], a[44:47]
	v_sub_f32_e32 v71, v90, v160
	v_add_f32_e32 v57, v67, v57
	v_mfma_f32_16x16x32_f16 a[0:3], a[132:135], v[40:43], a[0:3]
	v_exp_f32_e32 v71, v71
	v_sub_f32_e32 v72, v91, v160
	v_mfma_f32_16x16x32_f16 a[8:11], a[140:143], v[40:43], a[8:11]
	v_add_f32_e32 v57, v68, v57
	v_exp_f32_e32 v72, v72
	v_mfma_f32_16x16x32_f16 a[24:27], a[148:151], v[40:43], a[24:27]
	v_add_f32_e32 v57, v69, v57
	v_add_f32_e32 v57, v70, v57
	v_mfma_f32_16x16x32_f16 a[44:47], a[156:159], v[40:43], a[44:47]
	v_add_f32_e32 v57, v71, v57
	v_add_f32_e32 v57, v72, v57
	v_mfma_f32_16x16x32_f16 a[64:67], a[160:163], v[44:47], a[64:67]
	v_add_f32_e32 v243, v57, v243
	v_cvt_pk_f16_f32 v57, v67, v68
	v_mfma_f32_16x16x32_f16 a[76:79], a[168:171], v[44:47], a[76:79]
	v_cvt_pk_f16_f32 v58, v69, v70
	v_cvt_pk_f16_f32 v59, v71, v72
	v_mfma_f32_16x16x32_f16 a[92:95], a[176:179], v[44:47], a[92:95]
	v_sub_f32_e32 v32, v96, v112
	v_exp_f32_e32 v32, v32
	v_mfma_f32_16x16x32_f16 a[104:107], a[184:187], v[44:47], a[104:107]
	v_sub_f32_e32 v34, v97, v112
	v_exp_f32_e32 v34, v34
	v_mfma_f32_16x16x32_f16 a[64:67], a[164:167], v[40:43], a[64:67]
	v_sub_f32_e32 v35, v98, v112
	v_exp_f32_e32 v35, v35
	v_mfma_f32_16x16x32_f16 a[76:79], a[172:175], v[40:43], a[76:79]
	v_sub_f32_e32 v36, v99, v112
	v_exp_f32_e32 v36, v36
	v_mfma_f32_16x16x32_f16 a[92:95], a[180:183], v[40:43], a[92:95]
	v_sub_f32_e32 v37, v104, v112
	v_add_f32_e32 v33, 0, v32
	v_mfma_f32_16x16x32_f16 a[104:107], a[188:191], v[40:43], a[104:107]
	v_exp_f32_e32 v37, v37
	v_sub_f32_e32 v38, v105, v112
	v_mfma_f32_16x16x32_f16 a[4:7], a[128:131], v[60:63], a[4:7]
	v_add_f32_e32 v33, v34, v33
	v_exp_f32_e32 v38, v38
	v_mfma_f32_16x16x32_f16 a[16:19], a[136:139], v[60:63], a[16:19]
	v_sub_f32_e32 v39, v106, v112
	v_add_f32_e32 v33, v35, v33
	v_mfma_f32_16x16x32_f16 a[36:39], a[144:147], v[60:63], a[36:39]
	v_exp_f32_e32 v39, v39
	v_sub_f32_e32 v64, v107, v112
	v_mfma_f32_16x16x32_f16 a[52:55], a[152:155], v[60:63], a[52:55]
	v_add_f32_e32 v33, v36, v33
	v_exp_f32_e32 v64, v64
	v_mfma_f32_16x16x32_f16 a[4:7], a[132:135], v[56:59], a[4:7]
	v_sub_f32_e32 v65, v100, v112
	v_add_f32_e32 v33, v37, v33
	v_mfma_f32_16x16x32_f16 a[16:19], a[140:143], v[56:59], a[16:19]
	v_exp_f32_e32 v65, v65
	v_sub_f32_e32 v66, v101, v112
	v_mfma_f32_16x16x32_f16 a[36:39], a[148:151], v[56:59], a[36:39]
	v_add_f32_e32 v33, v38, v33
	v_exp_f32_e32 v66, v66
	v_mfma_f32_16x16x32_f16 a[52:55], a[156:159], v[56:59], a[52:55]
	v_sub_f32_e32 v67, v102, v112
	v_add_f32_e32 v33, v39, v33
	v_mfma_f32_16x16x32_f16 a[68:71], a[160:163], v[60:63], a[68:71]
	v_exp_f32_e32 v67, v67
	v_sub_f32_e32 v68, v103, v112
	v_mfma_f32_16x16x32_f16 a[84:87], a[168:171], v[60:63], a[84:87]
	v_add_f32_e32 v33, v64, v33
	v_exp_f32_e32 v68, v68
	v_mfma_f32_16x16x32_f16 a[100:103], a[176:179], v[60:63], a[100:103]
	v_sub_f32_e32 v69, v108, v112
	v_add_f32_e32 v33, v65, v33
	v_mfma_f32_16x16x32_f16 a[116:119], a[184:187], v[60:63], a[116:119]
	v_exp_f32_e32 v69, v69
	v_sub_f32_e32 v70, v109, v112
	v_mfma_f32_16x16x32_f16 a[68:71], a[164:167], v[56:59], a[68:71]
	v_add_f32_e32 v33, v66, v33
	v_exp_f32_e32 v70, v70
	v_mfma_f32_16x16x32_f16 a[84:87], a[172:175], v[56:59], a[84:87]
	v_sub_f32_e32 v71, v110, v112
	v_add_f32_e32 v33, v67, v33
	v_mfma_f32_16x16x32_f16 a[100:103], a[180:183], v[56:59], a[100:103]
	v_exp_f32_e32 v71, v71
	v_sub_f32_e32 v72, v111, v112
	v_mfma_f32_16x16x32_f16 a[116:119], a[188:191], v[56:59], a[116:119]
	v_add_f32_e32 v33, v68, v33
	v_exp_f32_e32 v72, v72
	v_add_f32_e32 v33, v69, v33
	v_add_f32_e32 v33, v70, v33
	v_cvt_pk_f16_f32 v39, v39, v64
	v_cvt_pk_f16_f32 v38, v37, v38
	v_cvt_pk_f16_f32 v37, v35, v36
	v_cvt_pk_f16_f32 v36, v32, v34
	v_cvt_pk_f16_f32 v32, v65, v66
	v_add_f32_e32 v33, v71, v33
	v_add_f32_e32 v33, v72, v33
	v_add_f32_e32 v233, v33, v233
	v_cvt_pk_f16_f32 v35, v71, v72
	v_cvt_pk_f16_f32 v34, v69, v70
	v_cvt_pk_f16_f32 v33, v67, v68
	s_nop 1
	s_waitcnt lgkmcnt(0)
	s_barrier
	v_mfma_f32_16x16x32_f16 a[20:23], a[128:131], v[36:39], a[20:23]
	v_mfma_f32_16x16x32_f16 a[32:35], a[136:139], v[36:39], a[32:35]
	v_mfma_f32_16x16x32_f16 a[48:51], a[144:147], v[36:39], a[48:51]
	v_mfma_f32_16x16x32_f16 a[60:63], a[152:155], v[36:39], a[60:63]
	v_mfma_f32_16x16x32_f16 a[20:23], a[132:135], v[32:35], a[20:23]
	v_mfma_f32_16x16x32_f16 a[32:35], a[140:143], v[32:35], a[32:35]
	v_mfma_f32_16x16x32_f16 a[48:51], a[148:151], v[32:35], a[48:51]
	v_mfma_f32_16x16x32_f16 a[60:63], a[156:159], v[32:35], a[60:63]
	v_mfma_f32_16x16x32_f16 a[80:83], a[160:163], v[36:39], a[80:83]
	v_mfma_f32_16x16x32_f16 a[96:99], a[168:171], v[36:39], a[96:99]
	v_mfma_f32_16x16x32_f16 a[112:115], a[176:179], v[36:39], a[112:115]
	v_mfma_f32_16x16x32_f16 a[124:127], a[184:187], v[36:39], a[124:127]
	v_mfma_f32_16x16x32_f16 a[80:83], a[164:167], v[32:35], a[80:83]
	v_mfma_f32_16x16x32_f16 a[96:99], a[172:175], v[32:35], a[96:99]
	v_mfma_f32_16x16x32_f16 a[112:115], a[180:183], v[32:35], a[112:115]
	v_mfma_f32_16x16x32_f16 a[124:127], a[188:191], v[32:35], a[124:127]
	s_add_i32 s20, s20, 64
	s_cmp_lg_u32 s73, s94
	s_cbranch_scc0 .LBB0_1978
	v_mov_b32_e32 v246, v112
	v_mov_b32_e32 v247, v144
	v_mov_b32_e32 v253, v160
	v_mov_b32_e32 v198, v176
	s_mov_b32 s16, s94
	s_branch .LBB0_1948
